# attention Y waits merged to one counted lgkmcnt per 4-MFMA group (X waits stay per-MFMA)
# baseline (speedup 1.0000x reference)
.LBB0_622:
	v_add3_u32 v165, s57, v143, v163
	ds_read_b128 v[190:193], v165 offset:18432
	ds_read_b128 v[194:197], v165 offset:18448
	ds_read_b128 v[128:131], v165 offset:23040
	ds_read_b128 v[132:135], v165 offset:23056
	ds_read_b128 v[136:139], v165 offset:27648
	ds_read_b128 v[166:169], v165 offset:27664
	ds_read_b128 v[170:173], v165 offset:32256
	ds_read_b128 v[178:181], v165 offset:32272
	v_exp_f32_e32 v96, v96
	v_exp_f32_e32 v97, v97
	v_exp_f32_e32 v98, v98
	v_exp_f32_e32 v99, v99
	v_exp_f32_e32 v100, v100
	v_add_f32_e32 v198, v97, v96
	v_exp_f32_e32 v101, v101
	v_add_f32_e32 v198, v98, v198
	v_exp_f32_e32 v102, v102
	v_add_f32_e32 v198, v99, v198
	v_exp_f32_e32 v103, v103
	v_add_f32_e32 v198, v100, v198
	v_exp_f32_e32 v104, v104
	v_add_f32_e32 v198, v101, v198
	v_exp_f32_e32 v105, v105
	v_add_f32_e32 v198, v102, v198
	v_exp_f32_e32 v106, v106
	v_add_f32_e32 v198, v103, v198
	v_exp_f32_e32 v107, v107
	v_add_f32_e32 v198, v104, v198
	v_exp_f32_e32 v108, v108
	v_add_f32_e32 v198, v105, v198
	v_exp_f32_e32 v109, v109
	v_add_f32_e32 v198, v106, v198
	v_exp_f32_e32 v110, v110
	v_add_f32_e32 v198, v107, v198
	v_exp_f32_e32 v111, v111
	v_add_f32_e32 v198, v108, v198
	v_add_f32_e32 v198, v109, v198
	v_add_f32_e32 v198, v110, v198
	v_add_f32_e32 v198, v111, v198
	v_add_f32_e32 v157, v157, v198
	v_cvt_pk_bf16_f32 v96, v96, v97
	v_cvt_pk_bf16_f32 v97, v98, v99
	v_cvt_pk_bf16_f32 v98, v100, v101
	v_cvt_pk_bf16_f32 v99, v102, v103
	v_cvt_pk_bf16_f32 v100, v104, v105
	v_cvt_pk_bf16_f32 v101, v106, v107
	v_cvt_pk_bf16_f32 v102, v108, v109
	v_cvt_pk_bf16_f32 v103, v110, v111
	s_waitcnt lgkmcnt(4)
	v_mfma_f32_32x32x16_bf16 v[48:63], v[190:193], v[96:99], v[48:63]
	v_exp_f32_e32 v174, v80
	v_exp_f32_e32 v175, v81
	v_exp_f32_e32 v182, v82
	v_exp_f32_e32 v183, v83
	v_add_f32_e32 v80, v175, v174
	v_add_f32_e32 v80, v182, v80
	v_mfma_f32_32x32x16_bf16 v[0:15], v[128:131], v[96:99], v[0:15]
	v_add_f32_e32 v80, v183, v80
	v_mfma_f32_32x32x16_bf16 v[48:63], v[194:197], v[100:103], v[48:63]
	v_exp_f32_e32 v128, v84
	v_exp_f32_e32 v129, v85
	v_exp_f32_e32 v130, v86
	v_exp_f32_e32 v131, v87
	v_add_f32_e32 v80, v128, v80
	v_add_f32_e32 v80, v129, v80
	v_add_f32_e32 v80, v130, v80
	v_mfma_f32_32x32x16_bf16 v[0:15], v[132:135], v[100:103], v[0:15]
	v_add_f32_e32 v184, v131, v80
	ds_read_b128 v[80:83], v165 offset:18496
	ds_read_b128 v[84:87], v165 offset:18512
	ds_read_b128 v[104:107], v165 offset:23104
	ds_read_b128 v[108:111], v165 offset:23120
	s_waitcnt lgkmcnt(4)
	v_mfma_f32_32x32x16_bf16 v[32:47], v[136:139], v[96:99], v[32:47]
	v_exp_f32_e32 v132, v88
	v_exp_f32_e32 v133, v89
	v_exp_f32_e32 v134, v90
	v_exp_f32_e32 v135, v91
	v_add_f32_e32 v88, v132, v184
	v_add_f32_e32 v88, v133, v88
	v_add_f32_e32 v88, v134, v88
	v_mfma_f32_32x32x16_bf16 v[16:31], v[170:173], v[96:99], v[16:31]
	v_add_f32_e32 v88, v135, v88
	v_exp_f32_e32 v96, v92
	v_mfma_f32_32x32x16_bf16 v[32:47], v[166:169], v[100:103], v[32:47]
	v_exp_f32_e32 v97, v93
	v_exp_f32_e32 v98, v94
	v_exp_f32_e32 v95, v95
	v_add_f32_e32 v88, v96, v88
	v_add_f32_e32 v88, v97, v88
	v_add_f32_e32 v88, v98, v88
	v_add_f32_e32 v88, v95, v88
	v_mfma_f32_32x32x16_bf16 v[16:31], v[178:181], v[100:103], v[16:31]
	v_add_f32_e32 v157, v157, v88
	v_cvt_pk_bf16_f32 v88, v174, v175
	v_cvt_pk_bf16_f32 v89, v182, v183
	v_cvt_pk_bf16_f32 v90, v128, v129
	v_cvt_pk_bf16_f32 v91, v130, v131
	v_cvt_pk_bf16_f32 v92, v132, v133
	v_cvt_pk_bf16_f32 v93, v134, v135
	v_cvt_pk_bf16_f32 v94, v96, v97
	v_cvt_pk_bf16_f32 v95, v98, v95
	ds_read_b128 v[96:99], v165 offset:27712
	ds_read_b128 v[100:103], v165 offset:27728
	ds_read_b128 v[128:131], v165 offset:32320
	ds_read_b128 v[132:135], v165 offset:32336
	s_waitcnt lgkmcnt(4)
	v_mfma_f32_32x32x16_bf16 v[48:63], v[80:83], v[88:91], v[48:63]
	v_mfma_f32_32x32x16_bf16 v[0:15], v[104:107], v[88:91], v[0:15]
	v_mfma_f32_32x32x16_bf16 v[48:63], v[84:87], v[92:95], v[48:63]
	v_mfma_f32_32x32x16_bf16 v[0:15], v[108:111], v[92:95], v[0:15]
	s_waitcnt lgkmcnt(0)
	v_mfma_f32_32x32x16_bf16 v[32:47], v[96:99], v[88:91], v[32:47]
	v_mfma_f32_32x32x16_bf16 v[16:31], v[128:131], v[88:91], v[16:31]
	v_mfma_f32_32x32x16_bf16 v[32:47], v[100:103], v[92:95], v[32:47]
	v_mfma_f32_32x32x16_bf16 v[16:31], v[132:135], v[92:95], v[16:31]
	s_add_i32 s4, s9, 0x9000
	s_cmp_lg_u32 s9, 0x12000
	s_cselect_b32 s9, s4, 0
	s_add_i32 s4, s56, 1
	s_cmp_lg_u32 s56, 2
	s_cselect_b32 s56, s4, 0
	s_add_i32 s8, s8, 1
	s_add_u32 s40, s40, 0x80
	s_addc_u32 s41, s41, 0
	s_add_u32 s46, s46, 0x60000
	s_waitcnt lgkmcnt(0)
	s_barrier
	s_addc_u32 s47, s47, 0
	s_add_i32 s87, s87, 64
	s_cmpk_lg_i32 s87, 0xfc0
	s_cbranch_scc0 .LBB0_633

.LBB0_643:
	v_add_u32_e32 v128, s50, v164
	s_waitcnt lgkmcnt(0)
	s_barrier
	v_add_u32_e32 v168, v128, v165
	ds_read_b128 v[140:143], v168 offset:18432
	ds_read_b128 v[132:135], v168 offset:18448
	ds_read_b128 v[136:139], v168 offset:23040
	ds_read_b128 v[128:131], v168 offset:23056
	ds_read_b128 v[178:181], v168 offset:27648
	ds_read_b128 v[182:185], v168 offset:27664
	ds_read_b128 v[186:189], v168 offset:32256
	ds_read_b128 v[190:193], v168 offset:32272
	v_exp_f32_e32 v96, v96
	v_exp_f32_e32 v97, v97
	v_exp_f32_e32 v98, v98
	v_exp_f32_e32 v99, v99
	v_exp_f32_e32 v100, v100
	v_exp_f32_e32 v101, v101
	v_exp_f32_e32 v102, v102
	v_exp_f32_e32 v103, v103
	v_exp_f32_e32 v104, v104
	v_exp_f32_e32 v105, v105
	v_exp_f32_e32 v106, v106
	v_exp_f32_e32 v107, v107
	v_exp_f32_e32 v108, v108
	v_exp_f32_e32 v109, v109
	v_exp_f32_e32 v110, v110
	v_exp_f32_e32 v111, v111
	v_cvt_pk_bf16_f32 v170, v96, v97
	v_cvt_pk_bf16_f32 v171, v98, v99
	v_cvt_pk_bf16_f32 v172, v100, v101
	v_cvt_pk_bf16_f32 v173, v102, v103
	v_cvt_pk_bf16_f32 v194, v104, v105
	v_cvt_pk_bf16_f32 v195, v106, v107
	v_cvt_pk_bf16_f32 v196, v108, v109
	v_cvt_pk_bf16_f32 v197, v110, v111
	s_waitcnt lgkmcnt(4)
	v_mfma_f32_32x32x16_bf16 v[48:63], v[140:143], v[170:173], v[48:63]
	v_exp_f32_e32 v80, v80
	v_exp_f32_e32 v81, v81
	v_exp_f32_e32 v82, v82
	v_exp_f32_e32 v83, v83
	v_mfma_f32_32x32x16_bf16 v[0:15], v[136:139], v[170:173], v[0:15]
	v_mfma_f32_32x32x16_bf16 v[48:63], v[132:135], v[194:197], v[48:63]
	v_exp_f32_e32 v84, v84
	v_exp_f32_e32 v85, v85
	v_exp_f32_e32 v86, v86
	v_exp_f32_e32 v87, v87
	v_mfma_f32_32x32x16_bf16 v[0:15], v[128:131], v[194:197], v[0:15]
	ds_read_b128 v[128:131], v168 offset:18496
	ds_read_b128 v[132:135], v168 offset:18512
	ds_read_b128 v[136:139], v168 offset:23104
	ds_read_b128 v[140:143], v168 offset:23120
	s_waitcnt lgkmcnt(4)
	v_mfma_f32_32x32x16_bf16 v[32:47], v[178:181], v[170:173], v[32:47]
	v_exp_f32_e32 v88, v88
	v_exp_f32_e32 v89, v89
	v_exp_f32_e32 v90, v90
	v_exp_f32_e32 v91, v91
	v_mfma_f32_32x32x16_bf16 v[16:31], v[186:189], v[170:173], v[16:31]
	v_mfma_f32_32x32x16_bf16 v[32:47], v[182:185], v[194:197], v[32:47]
	v_exp_f32_e32 v92, v92
	v_exp_f32_e32 v93, v93
	v_exp_f32_e32 v94, v94
	v_exp_f32_e32 v95, v95
	v_cvt_pk_bf16_f32 v170, v80, v81
	v_cvt_pk_bf16_f32 v171, v82, v83
	v_cvt_pk_bf16_f32 v172, v84, v85
	v_mfma_f32_32x32x16_bf16 v[16:31], v[190:193], v[194:197], v[16:31]
	v_cvt_pk_bf16_f32 v173, v86, v87
	v_cvt_pk_bf16_f32 v178, v88, v89
	v_cvt_pk_bf16_f32 v179, v90, v91
	v_cvt_pk_bf16_f32 v180, v92, v93
	v_cvt_pk_bf16_f32 v181, v94, v95
	ds_read_b128 v[182:185], v168 offset:27712
	ds_read_b128 v[186:189], v168 offset:27728
	ds_read_b128 v[190:193], v168 offset:32320
	ds_read_b128 v[194:197], v168 offset:32336
	s_cmp_gt_u32 s33, 61
	s_cselect_b64 s[50:51], -1, 0
	s_and_b64 vcc, exec, s[50:51]
	s_cbranch_vccnz .LBB0_645
	s_mul_i32 s63, s45, 0x9000
	s_or_b32 s64, s63, s35
	s_and_b64 s[60:61], s[54:55], exec
	s_cselect_b32 m0, s64, s82
	s_nop 0
	global_load_lds_dwordx4 v[240:241], off
	s_and_b64 s[60:61], s[38:39], exec
	s_cselect_b32 s60, s63, 0x12000
	s_add_i32 m0, s2, s60
	v_lshl_add_u64 v[240:241], v[240:241], 0, v[200:201]
	global_load_lds_dwordx4 v[242:243], off
	s_add_i32 s64, s63, s21
	s_and_b64 s[60:61], s[40:41], exec
	s_cselect_b32 m0, s64, s8
	v_lshl_add_u64 v[242:243], v[242:243], 0, v[202:203]
	global_load_lds_dwordx4 v[244:245], off
	s_and_b64 s[60:61], s[42:43], exec
	s_cselect_b32 s60, s63, 0x12000
	s_add_i32 m0, s26, s60
	v_lshl_add_u64 v[244:245], v[244:245], 0, v[204:205]
	global_load_lds_dwordx4 v[246:247], off
	s_add_i32 s63, s63, s3
	s_and_b64 s[60:61], s[46:47], exec
	s_cselect_b32 m0, s63, s9
	v_lshl_add_u64 v[246:247], v[246:247], 0, v[206:207]
	global_load_lds_dwordx4 v[248:249], off
	v_lshl_add_u64 v[248:249], v[248:249], 0, v[208:209]
.LBB0_645:
	s_waitcnt lgkmcnt(4)
	v_mfma_f32_32x32x16_bf16 v[48:63], v[128:131], v[170:173], v[48:63]
	v_add_f32_e32 v96, v97, v96
	v_add_f32_e32 v96, v98, v96
	v_add_f32_e32 v80, v81, v80
	v_add_f32_e32 v96, v99, v96
	v_mfma_f32_32x32x16_bf16 v[0:15], v[136:139], v[170:173], v[0:15]
	v_add_f32_e32 v80, v82, v80
	v_add_f32_e32 v96, v100, v96
	v_add_f32_e32 v80, v83, v80
	v_add_f32_e32 v96, v101, v96
	v_mfma_f32_32x32x16_bf16 v[48:63], v[132:135], v[178:181], v[48:63]
	v_add_f32_e32 v80, v84, v80
	v_add_f32_e32 v96, v102, v96
	v_add_f32_e32 v80, v85, v80
	v_add_f32_e32 v96, v103, v96
	v_mfma_f32_32x32x16_bf16 v[0:15], v[140:143], v[178:181], v[0:15]
	v_add_f32_e32 v80, v86, v80
	v_add_f32_e32 v96, v104, v96
	v_add_f32_e32 v80, v87, v80
	v_add_f32_e32 v96, v105, v96
	s_waitcnt lgkmcnt(0)
	v_mfma_f32_32x32x16_bf16 v[32:47], v[182:185], v[170:173], v[32:47]
	v_add_f32_e32 v80, v88, v80
	v_add_f32_e32 v96, v106, v96
	v_add_f32_e32 v80, v89, v80
	v_add_f32_e32 v96, v107, v96
	v_mfma_f32_32x32x16_bf16 v[16:31], v[190:193], v[170:173], v[16:31]
	v_add_f32_e32 v80, v90, v80
	v_add_f32_e32 v96, v108, v96
	v_add_f32_e32 v80, v91, v80
	v_add_f32_e32 v96, v109, v96
	v_mfma_f32_32x32x16_bf16 v[32:47], v[186:189], v[178:181], v[32:47]
	v_add_f32_e32 v80, v92, v80
	v_add_f32_e32 v96, v110, v96
	v_add_f32_e32 v80, v93, v80
	v_add_f32_e32 v96, v111, v96
	v_mfma_f32_32x32x16_bf16 v[16:31], v[194:197], v[178:181], v[16:31]
	v_add_f32_e32 v80, v94, v80
	v_add_f32_e32 v96, v157, v96
	v_add_f32_e32 v80, v95, v80
	v_add_f32_e32 v157, v96, v80
	s_mov_b64 s[60:61], -1
	s_and_b64 vcc, exec, s[50:51]
	s_cbranch_vccz .LBB0_647
	s_waitcnt vmcnt(0) lgkmcnt(0)
	s_barrier
	s_mov_b64 s[60:61], 0

.LBB0_683:
	v_add3_u32 v165, s57, v143, v163
	ds_read_b128 v[190:193], v165 offset:18432
	ds_read_b128 v[194:197], v165 offset:18448
	ds_read_b128 v[128:131], v165 offset:23040
	ds_read_b128 v[132:135], v165 offset:23056
	ds_read_b128 v[136:139], v165 offset:27648
	ds_read_b128 v[166:169], v165 offset:27664
	ds_read_b128 v[170:173], v165 offset:32256
	ds_read_b128 v[178:181], v165 offset:32272
	v_exp_f32_e32 v96, v96
	v_exp_f32_e32 v97, v97
	v_exp_f32_e32 v98, v98
	v_exp_f32_e32 v99, v99
	v_exp_f32_e32 v100, v100
	v_add_f32_e32 v198, v97, v96
	v_exp_f32_e32 v101, v101
	v_add_f32_e32 v198, v98, v198
	v_exp_f32_e32 v102, v102
	v_add_f32_e32 v198, v99, v198
	v_exp_f32_e32 v103, v103
	v_add_f32_e32 v198, v100, v198
	v_exp_f32_e32 v104, v104
	v_add_f32_e32 v198, v101, v198
	v_exp_f32_e32 v105, v105
	v_add_f32_e32 v198, v102, v198
	v_exp_f32_e32 v106, v106
	v_add_f32_e32 v198, v103, v198
	v_exp_f32_e32 v107, v107
	v_add_f32_e32 v198, v104, v198
	v_exp_f32_e32 v108, v108
	v_add_f32_e32 v198, v105, v198
	v_exp_f32_e32 v109, v109
	v_add_f32_e32 v198, v106, v198
	v_exp_f32_e32 v110, v110
	v_add_f32_e32 v198, v107, v198
	v_exp_f32_e32 v111, v111
	v_add_f32_e32 v198, v108, v198
	v_add_f32_e32 v198, v109, v198
	v_add_f32_e32 v198, v110, v198
	v_add_f32_e32 v198, v111, v198
	v_add_f32_e32 v157, v157, v198
	v_cvt_pk_bf16_f32 v96, v96, v97
	v_cvt_pk_bf16_f32 v97, v98, v99
	v_cvt_pk_bf16_f32 v98, v100, v101
	v_cvt_pk_bf16_f32 v99, v102, v103
	v_cvt_pk_bf16_f32 v100, v104, v105
	v_cvt_pk_bf16_f32 v101, v106, v107
	v_cvt_pk_bf16_f32 v102, v108, v109
	v_cvt_pk_bf16_f32 v103, v110, v111
	s_waitcnt lgkmcnt(4)
	v_mfma_f32_32x32x16_bf16 v[48:63], v[190:193], v[96:99], v[48:63]
	v_exp_f32_e32 v174, v80
	v_exp_f32_e32 v175, v81
	v_exp_f32_e32 v182, v82
	v_exp_f32_e32 v183, v83
	v_add_f32_e32 v80, v175, v174
	v_add_f32_e32 v80, v182, v80
	v_mfma_f32_32x32x16_bf16 v[0:15], v[128:131], v[96:99], v[0:15]
	v_add_f32_e32 v80, v183, v80
	v_mfma_f32_32x32x16_bf16 v[48:63], v[194:197], v[100:103], v[48:63]
	v_exp_f32_e32 v128, v84
	v_exp_f32_e32 v129, v85
	v_exp_f32_e32 v130, v86
	v_exp_f32_e32 v131, v87
	v_add_f32_e32 v80, v128, v80
	v_add_f32_e32 v80, v129, v80
	v_add_f32_e32 v80, v130, v80
	v_mfma_f32_32x32x16_bf16 v[0:15], v[132:135], v[100:103], v[0:15]
	v_add_f32_e32 v184, v131, v80
	ds_read_b128 v[80:83], v165 offset:18496
	ds_read_b128 v[84:87], v165 offset:18512
	ds_read_b128 v[104:107], v165 offset:23104
	ds_read_b128 v[108:111], v165 offset:23120
	s_waitcnt lgkmcnt(4)
	v_mfma_f32_32x32x16_bf16 v[32:47], v[136:139], v[96:99], v[32:47]
	v_exp_f32_e32 v132, v88
	v_exp_f32_e32 v133, v89
	v_exp_f32_e32 v134, v90
	v_exp_f32_e32 v135, v91
	v_add_f32_e32 v88, v132, v184
	v_add_f32_e32 v88, v133, v88
	v_add_f32_e32 v88, v134, v88
	v_mfma_f32_32x32x16_bf16 v[16:31], v[170:173], v[96:99], v[16:31]
	v_add_f32_e32 v88, v135, v88
	v_exp_f32_e32 v96, v92
	v_mfma_f32_32x32x16_bf16 v[32:47], v[166:169], v[100:103], v[32:47]
	v_exp_f32_e32 v97, v93
	v_exp_f32_e32 v98, v94
	v_exp_f32_e32 v95, v95
	v_add_f32_e32 v88, v96, v88
	v_add_f32_e32 v88, v97, v88
	v_add_f32_e32 v88, v98, v88
	v_add_f32_e32 v88, v95, v88
	v_mfma_f32_32x32x16_bf16 v[16:31], v[178:181], v[100:103], v[16:31]
	v_add_f32_e32 v157, v157, v88
	v_cvt_pk_bf16_f32 v88, v174, v175
	v_cvt_pk_bf16_f32 v89, v182, v183
	v_cvt_pk_bf16_f32 v90, v128, v129
	v_cvt_pk_bf16_f32 v91, v130, v131
	v_cvt_pk_bf16_f32 v92, v132, v133
	v_cvt_pk_bf16_f32 v93, v134, v135
	v_cvt_pk_bf16_f32 v94, v96, v97
	v_cvt_pk_bf16_f32 v95, v98, v95
	ds_read_b128 v[96:99], v165 offset:27712
	ds_read_b128 v[100:103], v165 offset:27728
	ds_read_b128 v[128:131], v165 offset:32320
	ds_read_b128 v[132:135], v165 offset:32336
	s_waitcnt lgkmcnt(4)
	v_mfma_f32_32x32x16_bf16 v[48:63], v[80:83], v[88:91], v[48:63]
	v_mfma_f32_32x32x16_bf16 v[0:15], v[104:107], v[88:91], v[0:15]
	v_mfma_f32_32x32x16_bf16 v[48:63], v[84:87], v[92:95], v[48:63]
	v_mfma_f32_32x32x16_bf16 v[0:15], v[108:111], v[92:95], v[0:15]
	s_waitcnt lgkmcnt(0)
	v_mfma_f32_32x32x16_bf16 v[32:47], v[96:99], v[88:91], v[32:47]
	v_mfma_f32_32x32x16_bf16 v[16:31], v[128:131], v[88:91], v[16:31]
	v_mfma_f32_32x32x16_bf16 v[32:47], v[100:103], v[92:95], v[32:47]
	v_mfma_f32_32x32x16_bf16 v[16:31], v[132:135], v[92:95], v[16:31]
	s_add_i32 s4, s9, 0x9000
	s_cmp_lg_u32 s9, 0x12000
	s_cselect_b32 s9, s4, 0
	s_add_i32 s4, s56, 1
	s_cmp_lg_u32 s56, 2
	s_cselect_b32 s56, s4, 0
	s_add_i32 s8, s8, 1
	s_add_u32 s76, s76, 0x80
	s_addc_u32 s77, s77, 0
	s_add_u32 s10, s10, 0x60000
	s_waitcnt lgkmcnt(0)
	s_barrier
	s_addc_u32 s11, s11, 0
	s_add_i32 s58, s58, 64
	s_cmpk_lg_i32 s58, 0x7c0
	s_cbranch_scc0 .LBB0_694

.LBB0_704:
	v_add_u32_e32 v128, s56, v164
	s_waitcnt lgkmcnt(0)
	s_barrier
	v_add_u32_e32 v168, v128, v165
	ds_read_b128 v[140:143], v168 offset:18432
	ds_read_b128 v[132:135], v168 offset:18448
	ds_read_b128 v[136:139], v168 offset:23040
	ds_read_b128 v[128:131], v168 offset:23056
	ds_read_b128 v[178:181], v168 offset:27648
	ds_read_b128 v[182:185], v168 offset:27664
	ds_read_b128 v[186:189], v168 offset:32256
	ds_read_b128 v[190:193], v168 offset:32272
	v_exp_f32_e32 v96, v96
	v_exp_f32_e32 v97, v97
	v_exp_f32_e32 v98, v98
	v_exp_f32_e32 v99, v99
	v_exp_f32_e32 v100, v100
	v_exp_f32_e32 v101, v101
	v_exp_f32_e32 v102, v102
	v_exp_f32_e32 v103, v103
	v_exp_f32_e32 v104, v104
	v_exp_f32_e32 v105, v105
	v_exp_f32_e32 v106, v106
	v_exp_f32_e32 v107, v107
	v_exp_f32_e32 v108, v108
	v_exp_f32_e32 v109, v109
	v_exp_f32_e32 v110, v110
	v_exp_f32_e32 v111, v111
	v_cvt_pk_bf16_f32 v170, v96, v97
	v_cvt_pk_bf16_f32 v171, v98, v99
	v_cvt_pk_bf16_f32 v172, v100, v101
	v_cvt_pk_bf16_f32 v173, v102, v103
	v_cvt_pk_bf16_f32 v194, v104, v105
	v_cvt_pk_bf16_f32 v195, v106, v107
	v_cvt_pk_bf16_f32 v196, v108, v109
	v_cvt_pk_bf16_f32 v197, v110, v111
	s_waitcnt lgkmcnt(4)
	v_mfma_f32_32x32x16_bf16 v[48:63], v[140:143], v[170:173], v[48:63]
	v_exp_f32_e32 v80, v80
	v_exp_f32_e32 v81, v81
	v_exp_f32_e32 v82, v82
	v_exp_f32_e32 v83, v83
	v_mfma_f32_32x32x16_bf16 v[0:15], v[136:139], v[170:173], v[0:15]
	v_mfma_f32_32x32x16_bf16 v[48:63], v[132:135], v[194:197], v[48:63]
	v_exp_f32_e32 v84, v84
	v_exp_f32_e32 v85, v85
	v_exp_f32_e32 v86, v86
	v_exp_f32_e32 v87, v87
	v_mfma_f32_32x32x16_bf16 v[0:15], v[128:131], v[194:197], v[0:15]
	ds_read_b128 v[128:131], v168 offset:18496
	ds_read_b128 v[132:135], v168 offset:18512
	ds_read_b128 v[136:139], v168 offset:23104
	ds_read_b128 v[140:143], v168 offset:23120
	s_waitcnt lgkmcnt(4)
	v_mfma_f32_32x32x16_bf16 v[32:47], v[178:181], v[170:173], v[32:47]
	v_exp_f32_e32 v88, v88
	v_exp_f32_e32 v89, v89
	v_exp_f32_e32 v90, v90
	v_exp_f32_e32 v91, v91
	v_mfma_f32_32x32x16_bf16 v[16:31], v[186:189], v[170:173], v[16:31]
	v_mfma_f32_32x32x16_bf16 v[32:47], v[182:185], v[194:197], v[32:47]
	v_exp_f32_e32 v92, v92
	v_exp_f32_e32 v93, v93
	v_exp_f32_e32 v94, v94
	v_exp_f32_e32 v95, v95
	v_cvt_pk_bf16_f32 v170, v80, v81
	v_cvt_pk_bf16_f32 v171, v82, v83
	v_cvt_pk_bf16_f32 v172, v84, v85
	v_mfma_f32_32x32x16_bf16 v[16:31], v[190:193], v[194:197], v[16:31]
	v_cvt_pk_bf16_f32 v173, v86, v87
	v_cvt_pk_bf16_f32 v178, v88, v89
	v_cvt_pk_bf16_f32 v179, v90, v91
	v_cvt_pk_bf16_f32 v180, v92, v93
	v_cvt_pk_bf16_f32 v181, v94, v95
	ds_read_b128 v[182:185], v168 offset:27712
	ds_read_b128 v[186:189], v168 offset:27728
	ds_read_b128 v[190:193], v168 offset:32320
	ds_read_b128 v[194:197], v168 offset:32336
	s_cmp_gt_u32 s33, 29
	s_cselect_b64 s[60:61], -1, 0
	s_and_b64 vcc, exec, s[60:61]
	s_cbranch_vccnz .LBB0_706
	s_mul_i32 s62, s45, 0x9000
	s_or_b32 s63, s62, s35
	s_and_b64 s[58:59], s[54:55], exec
	s_cselect_b32 m0, s63, s82
	s_nop 0
	global_load_lds_dwordx4 v[240:241], off
	s_and_b64 s[58:59], s[10:11], exec
	s_cselect_b32 s58, s62, 0x12000
	s_add_i32 m0, s2, s58
	v_lshl_add_u64 v[240:241], v[240:241], 0, v[200:201]
	global_load_lds_dwordx4 v[242:243], off
	s_add_i32 s63, s62, s21
	s_and_b64 s[58:59], s[38:39], exec
	s_cselect_b32 m0, s63, s8
	v_lshl_add_u64 v[242:243], v[242:243], 0, v[202:203]
	global_load_lds_dwordx4 v[244:245], off
	s_and_b64 s[58:59], s[42:43], exec
	s_cselect_b32 s58, s62, 0x12000
	s_add_i32 m0, s26, s58
	v_lshl_add_u64 v[244:245], v[244:245], 0, v[204:205]
	global_load_lds_dwordx4 v[246:247], off
	s_add_i32 s62, s62, s3
	s_and_b64 s[58:59], s[50:51], exec
	s_cselect_b32 m0, s62, s9
	v_lshl_add_u64 v[246:247], v[246:247], 0, v[206:207]
	global_load_lds_dwordx4 v[248:249], off
	v_lshl_add_u64 v[248:249], v[248:249], 0, v[208:209]
.LBB0_706:
	s_waitcnt lgkmcnt(4)
	v_mfma_f32_32x32x16_bf16 v[48:63], v[128:131], v[170:173], v[48:63]
	v_add_f32_e32 v96, v97, v96
	v_add_f32_e32 v96, v98, v96
	v_add_f32_e32 v80, v81, v80
	v_add_f32_e32 v96, v99, v96
	v_mfma_f32_32x32x16_bf16 v[0:15], v[136:139], v[170:173], v[0:15]
	v_add_f32_e32 v80, v82, v80
	v_add_f32_e32 v96, v100, v96
	v_add_f32_e32 v80, v83, v80
	v_add_f32_e32 v96, v101, v96
	v_mfma_f32_32x32x16_bf16 v[48:63], v[132:135], v[178:181], v[48:63]
	v_add_f32_e32 v80, v84, v80
	v_add_f32_e32 v96, v102, v96
	v_add_f32_e32 v80, v85, v80
	v_add_f32_e32 v96, v103, v96
	v_mfma_f32_32x32x16_bf16 v[0:15], v[140:143], v[178:181], v[0:15]
	v_add_f32_e32 v80, v86, v80
	v_add_f32_e32 v96, v104, v96
	v_add_f32_e32 v80, v87, v80
	v_add_f32_e32 v96, v105, v96
	s_waitcnt lgkmcnt(0)
	v_mfma_f32_32x32x16_bf16 v[32:47], v[182:185], v[170:173], v[32:47]
	v_add_f32_e32 v80, v88, v80
	v_add_f32_e32 v96, v106, v96
	v_add_f32_e32 v80, v89, v80
	v_add_f32_e32 v96, v107, v96
	v_mfma_f32_32x32x16_bf16 v[16:31], v[190:193], v[170:173], v[16:31]
	v_add_f32_e32 v80, v90, v80
	v_add_f32_e32 v96, v108, v96
	v_add_f32_e32 v80, v91, v80
	v_add_f32_e32 v96, v109, v96
	v_mfma_f32_32x32x16_bf16 v[32:47], v[186:189], v[178:181], v[32:47]
	v_add_f32_e32 v80, v92, v80
	v_add_f32_e32 v96, v110, v96
	v_add_f32_e32 v80, v93, v80
	v_add_f32_e32 v96, v111, v96
	v_mfma_f32_32x32x16_bf16 v[16:31], v[194:197], v[178:181], v[16:31]
	v_add_f32_e32 v80, v94, v80
	v_add_f32_e32 v96, v157, v96
	v_add_f32_e32 v80, v95, v80
	v_add_f32_e32 v157, v96, v80
	s_mov_b64 s[62:63], -1
	s_and_b64 vcc, exec, s[60:61]
	s_cbranch_vccz .LBB0_708
	s_waitcnt vmcnt(0) lgkmcnt(0)
	s_barrier
	s_mov_b64 s[62:63], 0
